# adds (on v135): sgu_unit issues spatial-weight, LN gain/bias and both stat-partial load groups at the unit start next to the gv tile loads (was 4 serial load->wait stages)
# speedup vs baseline: 1.0040x; 1.0040x over previous
; #define LAS __attribute__((address_space(3)))
; __device__ __forceinline__ unsigned cvt_pk_bf16(float lo, float hi) { const f32x2 v = {lo, hi}; const bf16x2_t b = __builtin_convertvector(v, bf16x2_t); return __builtin_bit_cast(unsigned, b); }
; __device__ __forceinline__ float bf_lo(unsigned u) { return __uint_as_float(u << 16); }
; __device__ __forceinline__ float bf_hi(unsigned u) { return __uint_as_float(u & 0xffff0000u); }
; template <bool STORE> __device__ __forceinline__ void sgu_unit(LAS unsigned char* lds, const bf16_t* GEL, const float* STAT, bf16_t* GU, const float* sw, const float* sb, const float* lng, const float* lnb, int unit, const int wave_s) {
;     ...
;     for (int i = 0; i < 8; ++i) { const int id = tid + 512 * i, t = id >> 5, s4 = (id & 31) * 4; const f32x4 v = *(const f32x4*)(sw + (size_t)g * 16384 + t * 128 + s4);
;         u32x2 w; w.x = cvt_pk_bf16(v[0], v[1]); w.y = cvt_pk_bf16(v[2], v[3]); *(LAS u32x2*)(lds + SG_WL + t * 272 + s4 * 2) = w; }
;     __syncthreads();
; #pragma unroll
;     for (int i = 0; i < 4; ++i) { const int id = tid + 512 * i, s = id >> 4, cc = (id & 15) * 8; const u32x4 v = gv4[i];
;         const float mean = st[2 * s], rstd = st[2 * s + 1];
;         const f32x4 g0 = *(const f32x4*)(lng + c0 + cc), g1 = *(const f32x4*)(lng + c0 + cc + 4), b0 = *(const f32x4*)(lnb + c0 + cc), b1 = *(const f32x4*)(lnb + c0 + cc + 4);
;         float x[8] = {bf_lo(v.x), bf_hi(v.x), bf_lo(v.y), bf_hi(v.y), bf_lo(v.z), bf_hi(v.z), bf_lo(v.w), bf_hi(v.w)};
; #pragma unroll
;         for (int k = 0; k < 8; ++k) { const float gg = k < 4 ? g0[k & 3] : g1[k & 3], bb = k < 4 ? b0[k & 3] : b1[k & 3]; const float y = (x[k] - mean) * rstd * gg + bb;
;             *(LAS bf16_t*)(lds + SG_GL + (cc + k) * 272 + s * 2) = (bf16_t)(cvt_pk_bf16(y, 0.f) & 0xffffu); } }
.LBB0_849:
	s_or_b64 exec, exec, s[34:35]
	s_waitcnt vmcnt(15)
	v_lshlrev_b32_e32 v42, 16, v31
	v_and_b32_e32 v31, 0xffff0000, v31
	v_lshlrev_b32_e32 v43, 16, v32
	v_and_b32_e32 v32, 0xffff0000, v32
	v_lshlrev_b32_e32 v44, 16, v33
	v_and_b32_e32 v33, 0xffff0000, v33
	v_bfe_u32 v46, v34, 5, 1
	v_ashrrev_i32_e32 v6, 3, v6
	v_and_b32_e32 v39, -2, v6
	v_lshl_or_b32 v6, v6, 2, 4
	s_waitcnt vmcnt(11)
	v_cvt_pk_bf16_f32 v8, v196, v197
	v_cvt_pk_bf16_f32 v9, v198, v199
	v_mad_u64_u32 v[10:11], s[34:35], v228, s45, v[174:175]
	ds_write_b64 v10, v[8:9]
	s_waitcnt vmcnt(10)
	v_cvt_pk_bf16_f32 v8, v200, v201
	v_cvt_pk_bf16_f32 v9, v202, v203
	v_mad_u64_u32 v[10:11], s[34:35], v229, s45, v[174:175]
	ds_write_b64 v10, v[8:9]
	s_waitcnt vmcnt(9)
	v_cvt_pk_bf16_f32 v8, v204, v205
	v_cvt_pk_bf16_f32 v9, v206, v207
	v_mad_u64_u32 v[10:11], s[34:35], v230, s45, v[174:175]
	ds_write_b64 v10, v[8:9]
	s_waitcnt vmcnt(8)
	v_cvt_pk_bf16_f32 v8, v208, v209
	v_cvt_pk_bf16_f32 v9, v210, v211
	v_mad_u64_u32 v[10:11], s[34:35], v231, s45, v[174:175]
	ds_write_b64 v10, v[8:9]
	s_waitcnt vmcnt(7)
	v_cvt_pk_bf16_f32 v8, v212, v213
	v_cvt_pk_bf16_f32 v9, v214, v215
	v_mad_u64_u32 v[10:11], s[34:35], v232, s45, v[174:175]
	ds_write_b64 v10, v[8:9]
	s_waitcnt vmcnt(6)
	v_cvt_pk_bf16_f32 v8, v216, v217
	v_cvt_pk_bf16_f32 v9, v218, v219
	v_mad_u64_u32 v[10:11], s[34:35], v233, s45, v[174:175]
	ds_write_b64 v10, v[8:9]
	s_waitcnt vmcnt(5)
	v_cvt_pk_bf16_f32 v8, v220, v221
	v_cvt_pk_bf16_f32 v9, v222, v223
	v_mad_u64_u32 v[10:11], s[34:35], v234, s45, v[174:175]
	ds_write_b64 v10, v[8:9]
	s_waitcnt vmcnt(4)
	v_cvt_pk_bf16_f32 v8, v224, v225
	v_cvt_pk_bf16_f32 v9, v226, v227
	v_mad_u64_u32 v[10:11], s[34:35], v235, s45, v[174:175]
	ds_write_b64 v10, v[8:9]
	s_add_i32 s34, 0, 0x11000
	v_lshlrev_b32_e32 v0, 2, v38
	v_lshl_add_u32 v7, v39, 2, s34
	v_add_u32_e32 v6, s34, v6
	s_waitcnt lgkmcnt(0)
	s_barrier
	ds_read_b32 v40, v7
	ds_read_b32 v41, v6
	v_lshlrev_b32_e32 v0, 16, v30
	v_and_b32_e32 v30, 0xffff0000, v30
	s_waitcnt lgkmcnt(1)
	v_sub_f32_e32 v0, v0, v40
	s_waitcnt lgkmcnt(0)
	v_mul_f32_e32 v0, v41, v0
	v_sub_f32_e32 v30, v30, v40
	v_mul_f32_e32 v30, v41, v30
	s_waitcnt vmcnt(0)
	v_fma_f32 v0, v0, v180, v188
	v_cvt_pk_bf16_f32 v45, v0, s0
	v_lshlrev_b32_e32 v240, 1, v38
	v_mul_u32_u24_e32 v0, 0x110, v38
	v_fma_f32 v30, v30, v181, v189
	v_xor_b32_e32 v241, v240, v39
	v_add3_u32 v38, 0, v241, v0
	v_cvt_pk_bf16_f32 v30, v30, s0
	ds_write_b16 v38, v30 offset:35088
	v_sub_f32_e32 v30, v42, v40
	v_mul_f32_e32 v30, v41, v30
	v_fma_f32 v30, v30, v182, v190
	v_cvt_pk_bf16_f32 v30, v30, s0
	ds_write_b16 v38, v30 offset:35360
	v_sub_f32_e32 v30, v31, v40
	v_mul_f32_e32 v30, v41, v30
	v_fma_f32 v30, v30, v183, v191
	v_cvt_pk_bf16_f32 v30, v30, s0
	ds_write_b16 v38, v30 offset:35632
	v_sub_f32_e32 v30, v43, v40
	v_mul_f32_e32 v30, v41, v30
	v_fma_f32 v30, v30, v176, v184
	v_cvt_pk_bf16_f32 v30, v30, s0
	ds_write_b16 v38, v30 offset:35904
	v_sub_f32_e32 v30, v32, v40
	v_mul_f32_e32 v30, v41, v30
	v_fma_f32 v30, v30, v177, v185
	v_cvt_pk_bf16_f32 v30, v30, s0
	ds_write_b16 v38, v30 offset:36176
	v_sub_f32_e32 v30, v44, v40
	v_mul_f32_e32 v30, v41, v30
	v_fma_f32 v30, v30, v178, v186
	v_cvt_pk_bf16_f32 v30, v30, s0
	ds_write_b16 v38, v30 offset:36448
	v_sub_f32_e32 v30, v33, v40
	v_mul_f32_e32 v30, v41, v30
	v_fma_f32 v30, v30, v179, v187
	v_cvt_pk_bf16_f32 v30, v30, s0
	ds_write_b16 v38, v30 offset:36720
	v_ashrrev_i32_e32 v30, 3, v37
	v_and_b32_e32 v31, -2, v30
	v_lshl_add_u32 v32, v31, 2, s34
	v_lshl_or_b32 v30, v30, 2, 4
	ds_read_b32 v32, v32
	v_add_u32_e32 v30, s34, v30
	ds_read_b32 v30, v30
	v_lshlrev_b32_e32 v33, 16, v26
	v_and_b32_e32 v26, 0xffff0000, v26
	s_waitcnt lgkmcnt(1)
	v_sub_f32_e32 v26, v26, v32
	v_lshlrev_b32_e32 v37, 16, v27
	s_waitcnt lgkmcnt(0)
	v_mul_f32_e32 v26, v30, v26
	v_fma_f32 v26, v181, v26, v189
	v_xor_b32_e32 v241, v240, v31
	v_add3_u32 v31, 0, v241, v0
	v_cvt_pk_bf16_f32 v26, v26, s0
	ds_write_b16 v38, v45 offset:34816
	ds_write_b16 v31, v26 offset:35088
	v_sub_f32_e32 v26, v37, v32
	v_mul_f32_e32 v26, v30, v26
	v_fma_f32 v26, v182, v26, v190
	v_and_b32_e32 v27, 0xffff0000, v27
	v_cvt_pk_bf16_f32 v26, v26, s0
	ds_write_b16 v31, v26 offset:35360
	v_sub_f32_e32 v26, v27, v32
	v_mul_f32_e32 v26, v30, v26
	v_fma_f32 v26, v183, v26, v191
	v_lshlrev_b32_e32 v38, 16, v28
	v_cvt_pk_bf16_f32 v26, v26, s0
	ds_write_b16 v31, v26 offset:35632
	v_sub_f32_e32 v26, v38, v32
	v_mul_f32_e32 v26, v30, v26
	v_fma_f32 v26, v176, v26, v184
	v_and_b32_e32 v28, 0xffff0000, v28
	v_cvt_pk_bf16_f32 v26, v26, s0
	ds_write_b16 v31, v26 offset:35904
	v_sub_f32_e32 v26, v28, v32
	v_mul_f32_e32 v26, v30, v26
	v_fma_f32 v26, v177, v26, v185
	v_lshlrev_b32_e32 v39, 16, v29
	v_cvt_pk_bf16_f32 v26, v26, s0
	ds_write_b16 v31, v26 offset:36176
	v_sub_f32_e32 v26, v39, v32
	v_mul_f32_e32 v26, v30, v26
	v_fma_f32 v26, v178, v26, v186
	v_and_b32_e32 v29, 0xffff0000, v29
	v_cvt_pk_bf16_f32 v26, v26, s0
	ds_write_b16 v31, v26 offset:36448
	v_sub_f32_e32 v26, v29, v32
	v_mul_f32_e32 v26, v30, v26
	v_fma_f32 v26, v179, v26, v187
	v_cvt_pk_bf16_f32 v26, v26, s0
	ds_write_b16 v31, v26 offset:36720
	v_ashrrev_i32_e32 v26, 3, v36
	v_and_b32_e32 v27, -2, v26
	v_lshl_add_u32 v28, v27, 2, s34
	v_lshl_or_b32 v26, v26, 2, 4
	ds_read_b32 v28, v28
	v_add_u32_e32 v26, s34, v26
	ds_read_b32 v26, v26
	v_lshlrev_b32_e32 v29, 16, v18
	v_and_b32_e32 v18, 0xffff0000, v18
	v_sub_f32_e32 v33, v33, v32
	s_waitcnt lgkmcnt(1)
	v_sub_f32_e32 v18, v18, v28
	v_mul_f32_e32 v33, v30, v33
	s_waitcnt lgkmcnt(0)
; #define LAS __attribute__((address_space(3)))
; __device__ __forceinline__ unsigned cvt_pk_bf16(float lo, float hi) { const f32x2 v = {lo, hi}; const bf16x2_t b = __builtin_convertvector(v, bf16x2_t); return __builtin_bit_cast(unsigned, b); }
; __device__ __forceinline__ float bf_lo(unsigned u) { return __uint_as_float(u << 16); }
; __device__ __forceinline__ float bf_hi(unsigned u) { return __uint_as_float(u & 0xffff0000u); }
; template <bool STORE> __device__ __forceinline__ void sgu_unit(LAS unsigned char* lds, const bf16_t* GEL, const float* STAT, bf16_t* GU, const float* sw, const float* sb, const float* lng, const float* lnb, int unit, const int wave_s) {
;     ...
;     for (int i = 0; i < 4; ++i) { const int id = tid + 512 * i, s = id >> 4, cc = (id & 15) * 8; const u32x4 v = gv4[i];
;         const float mean = st[2 * s], rstd = st[2 * s + 1];
;         const f32x4 g0 = *(const f32x4*)(lng + c0 + cc), g1 = *(const f32x4*)(lng + c0 + cc + 4), b0 = *(const f32x4*)(lnb + c0 + cc), b1 = *(const f32x4*)(lnb + c0 + cc + 4);
;         float x[8] = {bf_lo(v.x), bf_hi(v.x), bf_lo(v.y), bf_hi(v.y), bf_lo(v.z), bf_hi(v.z), bf_lo(v.w), bf_hi(v.w)};
; #pragma unroll
;         for (int k = 0; k < 8; ++k) { const float gg = k < 4 ? g0[k & 3] : g1[k & 3], bb = k < 4 ? b0[k & 3] : b1[k & 3]; const float y = (x[k] - mean) * rstd * gg + bb;
;             *(LAS bf16_t*)(lds + SG_GL + (cc + k) * 272 + s * 2) = (bf16_t)(cvt_pk_bf16(y, 0.f) & 0xffffu); } }
;     __syncthreads();
;     const int cb = wid & 3, th = wid >> 2, q = lane & 31, hi = lane >> 5;
;     f32x16 d0 = {}, d1 = {};
; #pragma unroll
;     for (int ks = 0; ks < 8; ++ks) {
;         const bf16x8 af = *(const LAS bf16x8*)(lds + SG_GL + (32 * cb + q) * 272 + (16 * ks + 8 * hi) * 2);
;         const bf16x8 b0 = *(const LAS bf16x8*)(lds + SG_WL + (64 * th + q) * 272 + (16 * ks + 8 * hi) * 2);
;         const bf16x8 b1 = *(const LAS bf16x8*)(lds + SG_WL + (64 * th + 32 + q) * 272 + (16 * ks + 8 * hi) * 2);
;         d0 = __builtin_amdgcn_mfma_f32_32x32x16_bf16(af, b0, d0, 0, 0, 0);
;         d1 = __builtin_amdgcn_mfma_f32_32x32x16_bf16(af, b1, d1, 0, 0, 0);
;     }
	v_mul_f32_e32 v18, v26, v18
	v_fma_f32 v33, v180, v33, v188
	v_fma_f32 v18, v181, v18, v189
	v_cvt_pk_bf16_f32 v33, v33, s0
	v_lshlrev_b32_e32 v30, 16, v19
	v_xor_b32_e32 v241, v240, v27
	v_add3_u32 v27, 0, v241, v0
	v_cvt_pk_bf16_f32 v18, v18, s0
	ds_write_b16 v31, v33 offset:34816
	ds_write_b16 v27, v18 offset:35088
	v_sub_f32_e32 v18, v30, v28
	v_mul_f32_e32 v18, v26, v18
	v_fma_f32 v18, v182, v18, v190
	v_and_b32_e32 v19, 0xffff0000, v19
	v_cvt_pk_bf16_f32 v18, v18, s0
	ds_write_b16 v27, v18 offset:35360
	v_sub_f32_e32 v18, v19, v28
	v_mul_f32_e32 v18, v26, v18
	v_fma_f32 v18, v183, v18, v191
	v_lshlrev_b32_e32 v31, 16, v20
	v_cvt_pk_bf16_f32 v18, v18, s0
	ds_write_b16 v27, v18 offset:35632
	v_sub_f32_e32 v18, v31, v28
	v_mul_f32_e32 v18, v26, v18
	v_fma_f32 v18, v176, v18, v184
	v_and_b32_e32 v20, 0xffff0000, v20
	v_cvt_pk_bf16_f32 v18, v18, s0
	ds_write_b16 v27, v18 offset:35904
	v_sub_f32_e32 v18, v20, v28
	v_mul_f32_e32 v18, v26, v18
	v_fma_f32 v18, v177, v18, v185
	v_lshlrev_b32_e32 v32, 16, v21
	v_cvt_pk_bf16_f32 v18, v18, s0
	ds_write_b16 v27, v18 offset:36176
	v_sub_f32_e32 v18, v32, v28
	v_mul_f32_e32 v18, v26, v18
	v_fma_f32 v18, v178, v18, v186
	v_and_b32_e32 v21, 0xffff0000, v21
	v_cvt_pk_bf16_f32 v18, v18, s0
	ds_write_b16 v27, v18 offset:36448
	v_sub_f32_e32 v18, v21, v28
	v_mul_f32_e32 v18, v26, v18
	v_fma_f32 v18, v179, v18, v187
	v_ashrrev_i32_e32 v19, 3, v35
	v_cvt_pk_bf16_f32 v18, v18, s0
	v_and_b32_e32 v20, -2, v19
	ds_write_b16 v27, v18 offset:36720
	v_lshl_add_u32 v18, v20, 2, s34
	v_lshl_or_b32 v19, v19, 2, 4
	ds_read_b32 v18, v18
	v_add_u32_e32 v19, s34, v19
	ds_read_b32 v19, v19
	v_lshlrev_b32_e32 v21, 16, v2
	v_and_b32_e32 v2, 0xffff0000, v2
	v_sub_f32_e32 v29, v29, v28
	s_waitcnt lgkmcnt(1)
	v_sub_f32_e32 v2, v2, v18
	v_mul_f32_e32 v29, v26, v29
	s_waitcnt lgkmcnt(0)
	v_mul_f32_e32 v2, v19, v2
	v_fma_f32 v29, v180, v29, v188
	v_fma_f32 v2, v181, v2, v189
	v_cvt_pk_bf16_f32 v29, v29, s0
	v_lshlrev_b32_e32 v26, 16, v3
	v_xor_b32_e32 v241, v240, v20
	v_add3_u32 v0, 0, v241, v0
	v_cvt_pk_bf16_f32 v2, v2, s0
	ds_write_b16 v27, v29 offset:34816
	ds_write_b16 v0, v2 offset:35088
	v_sub_f32_e32 v2, v26, v18
	v_mul_f32_e32 v2, v19, v2
	v_fma_f32 v2, v182, v2, v190
	v_and_b32_e32 v3, 0xffff0000, v3
	v_cvt_pk_bf16_f32 v2, v2, s0
	ds_write_b16 v0, v2 offset:35360
	v_sub_f32_e32 v2, v3, v18
	v_mul_f32_e32 v2, v19, v2
	v_fmac_f32_e32 v191, v183, v2
	v_lshlrev_b32_e32 v27, 16, v4
	v_cvt_pk_bf16_f32 v2, v191, s0
	ds_write_b16 v0, v2 offset:35632
	v_sub_f32_e32 v2, v27, v18
	v_mul_f32_e32 v2, v19, v2
	v_fma_f32 v2, v176, v2, v184
	v_and_b32_e32 v4, 0xffff0000, v4
	v_cvt_pk_bf16_f32 v2, v2, s0
	ds_write_b16 v0, v2 offset:35904
	v_sub_f32_e32 v2, v4, v18
	v_mul_f32_e32 v2, v19, v2
	v_fma_f32 v2, v177, v2, v185
	v_lshlrev_b32_e32 v28, 16, v5
	v_cvt_pk_bf16_f32 v2, v2, s0
	ds_write_b16 v0, v2 offset:36176
	v_sub_f32_e32 v2, v28, v18
	v_mul_f32_e32 v2, v19, v2
	v_fma_f32 v2, v178, v2, v186
	v_and_b32_e32 v5, 0xffff0000, v5
	v_cvt_pk_bf16_f32 v2, v2, s0
	v_sub_f32_e32 v21, v21, v18
	ds_write_b16 v0, v2 offset:36448
	v_sub_f32_e32 v2, v5, v18
	v_mul_f32_e32 v21, v19, v21
	v_mul_f32_e32 v2, v19, v2
	v_fma_f32 v180, v180, v21, v188
	v_fmac_f32_e32 v187, v179, v2
	v_cvt_pk_bf16_f32 v180, v180, s0
	v_cvt_pk_bf16_f32 v2, v187, s0
	ds_write_b16 v0, v180 offset:34816
	ds_write_b16 v0, v2 offset:36720
	v_and_b32_e32 v0, 31, v34
	v_readlane_b32 s34, v253, 18
	v_lshlrev_b32_e32 v3, 4, v46
	s_waitcnt lgkmcnt(0)
	v_or_b32_e32 v2, s34, v0
	v_readlane_b32 s34, v253, 30
	v_lshrrev_b32_e32 v242, 3, v2
	v_mul_u32_u24_e32 v2, 0x110, v2
	s_barrier
	v_or_b32_e32 v47, s34, v0
	v_mul_lo_u32 v0, v47, s45
	v_add3_u32 v0, 0, v0, v3
	v_add3_u32 v48, 0, v2, v3
	v_and_b32_e32 v243, 1, v242
	v_xor_b32_e32 v243, v243, v46
	v_lshrrev_b32_e32 v242, 1, v242
	v_lshl_add_u32 v244, v243, 4, v2
	ds_read_b128 v[2:5], v0 offset:8704
	v_xor_b32_e32 v245, 0, v242
	v_lshl_add_u32 v245, v245, 5, v244
	ds_read_b128 v[6:9], v245 offset:34816
	v_xor_b32_e32 v245, 1, v242
	v_lshl_add_u32 v245, v245, 5, v244
	ds_read_b128 v[34:37], v245 offset:34816
	ds_read_b128 v[10:13], v0
	ds_read_b128 v[38:41], v0 offset:32
	s_waitcnt lgkmcnt(1)
	v_mfma_f32_32x32x16_bf16 v[18:33], v[6:9], v[10:13], 0
	ds_read_b128 v[42:45], v0 offset:8736
	s_lshl_b32 s34, s44, 1
	s_add_u32 s34, s40, s34
	s_addc_u32 s35, s41, 0
	v_mfma_f32_32x32x16_bf16 v[2:17], v[6:9], v[2:5], 0
	s_waitcnt lgkmcnt(1)
	v_mfma_f32_32x32x16_bf16 v[18:33], v[34:37], v[38:41], v[18:33]
	s_waitcnt lgkmcnt(0)
	v_mfma_f32_32x32x16_bf16 v[2:17], v[34:37], v[42:45], v[2:17]
	v_xor_b32_e32 v245, 2, v242
	v_lshl_add_u32 v245, v245, 5, v244
	ds_read_b128 v[34:37], v245 offset:34816
	ds_read_b128 v[38:41], v0 offset:64
	ds_read_b128 v[42:45], v0 offset:8768
	s_waitcnt lgkmcnt(1)
	v_mfma_f32_32x32x16_bf16 v[18:33], v[34:37], v[38:41], v[18:33]
	s_waitcnt lgkmcnt(0)
	v_mfma_f32_32x32x16_bf16 v[2:17], v[34:37], v[42:45], v[2:17]
	v_xor_b32_e32 v245, 3, v242
	v_lshl_add_u32 v245, v245, 5, v244
	ds_read_b128 v[34:37], v245 offset:34816
	ds_read_b128 v[38:41], v0 offset:96
	ds_read_b128 v[42:45], v0 offset:8800
	s_waitcnt lgkmcnt(1)
	v_mfma_f32_32x32x16_bf16 v[18:33], v[34:37], v[38:41], v[18:33]
	s_waitcnt lgkmcnt(0)
	v_mfma_f32_32x32x16_bf16 v[2:17], v[34:37], v[42:45], v[2:17]
	v_xor_b32_e32 v245, 4, v242
	v_lshl_add_u32 v245, v245, 5, v244
	ds_read_b128 v[34:37], v245 offset:34816
	ds_read_b128 v[38:41], v0 offset:128
	ds_read_b128 v[42:45], v0 offset:8832
	s_waitcnt lgkmcnt(1)
	v_mfma_f32_32x32x16_bf16 v[18:33], v[34:37], v[38:41], v[18:33]
	s_waitcnt lgkmcnt(0)
; #define LAS __attribute__((address_space(3)))
; __device__ __forceinline__ unsigned cvt_pk_bf16(float lo, float hi) { const f32x2 v = {lo, hi}; const bf16x2_t b = __builtin_convertvector(v, bf16x2_t); return __builtin_bit_cast(unsigned, b); }
; __device__ __forceinline__ float bf_lo(unsigned u) { return __uint_as_float(u << 16); }
; __device__ __forceinline__ float bf_hi(unsigned u) { return __uint_as_float(u & 0xffff0000u); }
; template <bool STORE> __device__ __forceinline__ void sgu_unit(LAS unsigned char* lds, const bf16_t* GEL, const float* STAT, bf16_t* GU, const float* sw, const float* sb, const float* lng, const float* lnb, int unit, const int wave_s) {
;     ...
;     for (int ks = 0; ks < 8; ++ks) {
;         const bf16x8 af = *(const LAS bf16x8*)(lds + SG_GL + (32 * cb + q) * 272 + (16 * ks + 8 * hi) * 2);
;         const bf16x8 b0 = *(const LAS bf16x8*)(lds + SG_WL + (64 * th + q) * 272 + (16 * ks + 8 * hi) * 2);
;         const bf16x8 b1 = *(const LAS bf16x8*)(lds + SG_WL + (64 * th + 32 + q) * 272 + (16 * ks + 8 * hi) * 2);
;         d0 = __builtin_amdgcn_mfma_f32_32x32x16_bf16(af, b0, d0, 0, 0, 0);
;         d1 = __builtin_amdgcn_mfma_f32_32x32x16_bf16(af, b1, d1, 0, 0, 0);
;     }
; #pragma unroll
;     for (int tb = 0; tb < 2; ++tb) { const int t = 64 * th + 32 * tb + q; const float bias = sb[g * 128 + t];
;         bf16_t* rowp = GU + (size_t)(tok0 + t) * DM + c0 + 32 * cb + 4 * hi;
; #pragma unroll
;         for (int i = 0; i < 4; ++i) { const u32x2 u = *(const u32x2*)(rowp + 8 * i);
;             const float m0 = (tb ? d1[4 * i] : d0[4 * i]) + bias, m1 = (tb ? d1[4 * i + 1] : d0[4 * i + 1]) + bias, m2 = (tb ? d1[4 * i + 2] : d0[4 * i + 2]) + bias, m3 = (tb ? d1[4 * i + 3] : d0[4 * i + 3]) + bias;
;             u32x2 w; w.x = cvt_pk_bf16(bf_lo(u.x) * m0, bf_hi(u.x) * m1); w.y = cvt_pk_bf16(bf_lo(u.y) * m2, bf_hi(u.y) * m3);
;             if (STORE) *(u32x2*)(rowp + 8 * i) = w; } }
;     __syncthreads();
	v_mfma_f32_32x32x16_bf16 v[2:17], v[34:37], v[42:45], v[2:17]
	v_xor_b32_e32 v245, 5, v242
	v_lshl_add_u32 v245, v245, 5, v244
	ds_read_b128 v[34:37], v245 offset:34816
	ds_read_b128 v[38:41], v0 offset:160
	ds_read_b128 v[42:45], v0 offset:8864
	s_waitcnt lgkmcnt(1)
	v_mfma_f32_32x32x16_bf16 v[18:33], v[34:37], v[38:41], v[18:33]
	s_waitcnt lgkmcnt(0)
	v_mfma_f32_32x32x16_bf16 v[2:17], v[34:37], v[42:45], v[2:17]
	v_xor_b32_e32 v245, 6, v242
	v_lshl_add_u32 v245, v245, 5, v244
	ds_read_b128 v[34:37], v245 offset:34816
	ds_read_b128 v[38:41], v0 offset:192
	ds_read_b128 v[42:45], v0 offset:8896
	s_waitcnt lgkmcnt(1)
	v_mfma_f32_32x32x16_bf16 v[18:33], v[34:37], v[38:41], v[18:33]
	s_waitcnt lgkmcnt(0)
	v_mfma_f32_32x32x16_bf16 v[2:17], v[34:37], v[42:45], v[2:17]
	v_xor_b32_e32 v245, 7, v242
	v_lshl_add_u32 v245, v245, 5, v244
	ds_read_b128 v[34:37], v245 offset:34816
	ds_read_b128 v[38:41], v0 offset:224
	ds_read_b128 v[42:45], v0 offset:8928
	v_lshlrev_b32_e32 v0, 3, v46
	s_waitcnt lgkmcnt(1)
	v_mfma_f32_32x32x16_bf16 v[18:33], v[34:37], v[38:41], v[18:33]
	v_add_u32_e32 v38, s43, v47
	v_ashrrev_i32_e32 v39, 31, v38
	v_lshlrev_b64 v[40:41], 11, v[38:39]
	s_waitcnt lgkmcnt(0)
	v_mfma_f32_32x32x16_bf16 v[2:17], v[34:37], v[42:45], v[2:17]
	v_lshl_add_u64 v[34:35], s[34:35], 0, v[0:1]
	v_add_u32_e32 v0, s44, v47
	v_lshl_add_u64 v[36:37], v[0:1], 2, s[12:13]
	v_lshl_add_u64 v[40:41], v[34:35], 0, v[40:41]
	v_add_u32_e32 v170, 32, v38
	v_ashrrev_i32_e32 v171, 31, v170
	v_lshlrev_b64 v[170:171], 11, v[170:171]
	v_lshl_add_u64 v[170:171], v[34:35], 0, v[170:171]
	global_load_dword v168, v[36:37], off
	global_load_dwordx2 v[150:151], v[40:41], off
	global_load_dwordx2 v[152:153], v[40:41], off offset:16
	global_load_dwordx2 v[154:155], v[40:41], off offset:32
	global_load_dwordx2 v[156:157], v[40:41], off offset:48
	global_load_dword v169, v[36:37], off offset:128
	global_load_dwordx2 v[158:159], v[170:171], off
	global_load_dwordx2 v[160:161], v[170:171], off offset:16
	global_load_dwordx2 v[162:163], v[170:171], off offset:32
	global_load_dwordx2 v[164:165], v[170:171], off offset:48
	s_waitcnt vmcnt(8)
	v_add_f32_e32 v18, v18, v168
	v_add_f32_e32 v19, v19, v168
	v_add_f32_e32 v20, v20, v168
	v_add_f32_e32 v21, v21, v168
	v_lshlrev_b32_e32 v172, 16, v150
	v_and_b32_e32 v173, 0xffff0000, v150
	v_mul_f32_e32 v18, v18, v172
	v_mul_f32_e32 v19, v19, v173
	v_lshlrev_b32_e32 v172, 16, v151
	v_and_b32_e32 v173, 0xffff0000, v151
	v_mul_f32_e32 v20, v20, v172
	v_mul_f32_e32 v21, v21, v173
	v_cvt_pk_bf16_f32 v18, v18, v19
	v_cvt_pk_bf16_f32 v19, v20, v21
	global_store_dwordx2 v[40:41], v[18:19], off
	s_waitcnt vmcnt(8)
	v_add_f32_e32 v22, v22, v168
	v_add_f32_e32 v23, v23, v168
	v_add_f32_e32 v24, v24, v168
	v_add_f32_e32 v25, v25, v168
	v_lshlrev_b32_e32 v172, 16, v152
	v_and_b32_e32 v173, 0xffff0000, v152
	v_mul_f32_e32 v22, v22, v172
	v_mul_f32_e32 v23, v23, v173
	v_lshlrev_b32_e32 v172, 16, v153
	v_and_b32_e32 v173, 0xffff0000, v153
	v_mul_f32_e32 v24, v24, v172
	v_mul_f32_e32 v25, v25, v173
	v_cvt_pk_bf16_f32 v22, v22, v23
	v_cvt_pk_bf16_f32 v23, v24, v25
	global_store_dwordx2 v[40:41], v[22:23], off offset:16
	s_waitcnt vmcnt(8)
	v_add_f32_e32 v26, v26, v168
	v_add_f32_e32 v27, v27, v168
	v_add_f32_e32 v28, v28, v168
	v_add_f32_e32 v29, v29, v168
	v_lshlrev_b32_e32 v172, 16, v154
	v_and_b32_e32 v173, 0xffff0000, v154
	v_mul_f32_e32 v26, v26, v172
	v_mul_f32_e32 v27, v27, v173
	v_lshlrev_b32_e32 v172, 16, v155
	v_and_b32_e32 v173, 0xffff0000, v155
	v_mul_f32_e32 v28, v28, v172
	v_mul_f32_e32 v29, v29, v173
	v_cvt_pk_bf16_f32 v26, v26, v27
	v_cvt_pk_bf16_f32 v27, v28, v29
	global_store_dwordx2 v[40:41], v[26:27], off offset:32
	s_waitcnt vmcnt(8)
	v_add_f32_e32 v30, v30, v168
	v_add_f32_e32 v31, v31, v168
	v_add_f32_e32 v32, v32, v168
	v_add_f32_e32 v33, v33, v168
	v_lshlrev_b32_e32 v172, 16, v156
	v_and_b32_e32 v173, 0xffff0000, v156
	v_mul_f32_e32 v30, v30, v172
	v_mul_f32_e32 v31, v31, v173
	v_lshlrev_b32_e32 v172, 16, v157
	v_and_b32_e32 v173, 0xffff0000, v157
	v_mul_f32_e32 v32, v32, v172
	v_mul_f32_e32 v33, v33, v173
	v_cvt_pk_bf16_f32 v30, v30, v31
	v_cvt_pk_bf16_f32 v31, v32, v33
	global_store_dwordx2 v[40:41], v[30:31], off offset:48
	s_waitcnt vmcnt(7)
	v_add_f32_e32 v2, v2, v169
	v_add_f32_e32 v3, v3, v169
	v_add_f32_e32 v4, v4, v169
	v_add_f32_e32 v5, v5, v169
	v_lshlrev_b32_e32 v172, 16, v158
	v_and_b32_e32 v173, 0xffff0000, v158
	v_mul_f32_e32 v2, v2, v172
	v_mul_f32_e32 v3, v3, v173
	v_lshlrev_b32_e32 v172, 16, v159
	v_and_b32_e32 v173, 0xffff0000, v159
	v_mul_f32_e32 v4, v4, v172
	v_mul_f32_e32 v5, v5, v173
	v_cvt_pk_bf16_f32 v2, v2, v3
	v_cvt_pk_bf16_f32 v3, v4, v5
	global_store_dwordx2 v[170:171], v[2:3], off
	s_waitcnt vmcnt(7)
	v_add_f32_e32 v6, v6, v169
	v_add_f32_e32 v7, v7, v169
	v_add_f32_e32 v8, v8, v169
	v_add_f32_e32 v9, v9, v169
	v_lshlrev_b32_e32 v172, 16, v160
	v_and_b32_e32 v173, 0xffff0000, v160
	v_mul_f32_e32 v6, v6, v172
	v_mul_f32_e32 v7, v7, v173
	v_lshlrev_b32_e32 v172, 16, v161
	v_and_b32_e32 v173, 0xffff0000, v161
	v_mul_f32_e32 v8, v8, v172
	v_mul_f32_e32 v9, v9, v173
	v_cvt_pk_bf16_f32 v6, v6, v7
	v_cvt_pk_bf16_f32 v7, v8, v9
	global_store_dwordx2 v[170:171], v[6:7], off offset:16
	s_waitcnt vmcnt(7)
	v_add_f32_e32 v10, v10, v169
	v_add_f32_e32 v11, v11, v169
	v_add_f32_e32 v12, v12, v169
	v_add_f32_e32 v13, v13, v169
	v_lshlrev_b32_e32 v172, 16, v162
	v_and_b32_e32 v173, 0xffff0000, v162
	v_mul_f32_e32 v10, v10, v172
	v_mul_f32_e32 v11, v11, v173
	v_lshlrev_b32_e32 v172, 16, v163
	v_and_b32_e32 v173, 0xffff0000, v163
	v_mul_f32_e32 v12, v12, v172
	v_mul_f32_e32 v13, v13, v173
	v_cvt_pk_bf16_f32 v10, v10, v11
	v_cvt_pk_bf16_f32 v11, v12, v13
	global_store_dwordx2 v[170:171], v[10:11], off offset:32
	s_waitcnt vmcnt(7)
	v_add_f32_e32 v14, v14, v169
	v_add_f32_e32 v15, v15, v169
	v_add_f32_e32 v16, v16, v169
	v_add_f32_e32 v17, v17, v169
	v_lshlrev_b32_e32 v172, 16, v164
	v_and_b32_e32 v173, 0xffff0000, v164
	v_mul_f32_e32 v14, v14, v172
	v_mul_f32_e32 v15, v15, v173
	v_lshlrev_b32_e32 v172, 16, v165
	v_and_b32_e32 v173, 0xffff0000, v165
	v_mul_f32_e32 v16, v16, v172
	v_mul_f32_e32 v17, v17, v173
	v_cvt_pk_bf16_f32 v14, v14, v15
	v_cvt_pk_bf16_f32 v15, v16, v17
	global_store_dwordx2 v[170:171], v[14:15], off offset:48
	s_barrier

; #define LAS __attribute__((address_space(3)))
; __device__ __forceinline__ unsigned cvt_pk_bf16(float lo, float hi) { const f32x2 v = {lo, hi}; const bf16x2_t b = __builtin_convertvector(v, bf16x2_t); return __builtin_bit_cast(unsigned, b); }
; template <bool STORE> __device__ __forceinline__ void sgu_unit(LAS unsigned char* lds, const bf16_t* GEL, const float* STAT, bf16_t* GU, const float* sw, const float* sb, const float* lng, const float* lnb, int unit, const int wave_s) {
;     ...
;     const int chunk = unit >> 3, g = unit & 7, tok0 = chunk * 128, c0 = g * 128;
;     LAS float* st = (LAS float*)(lds + SG_ST);
;     u32x4 gv4[4];
; #pragma unroll
;     for (int i = 0; i < 4; ++i) { const int id = tid + 512 * i; gv4[i] = *(const u32x4*)(GEL + (size_t)(tok0 + (id >> 4)) * DM + c0 + (id & 15) * 8); }
;     if (tid < 128) { const f32x4* sp = (const f32x4*)(STAT + (size_t)(tok0 + tid) * 32); float s = 0.f, s2 = 0.f;
; #pragma unroll
;         for (int i = 0; i < 8; ++i) { const f32x4 v = sp[i]; s += v[0] + v[2]; s2 += v[1] + v[3]; }
;         const float mean = s * (1.f / DM), var = s2 * (1.f / DM) - mean * mean; st[2 * tid] = mean; st[2 * tid + 1] = __builtin_amdgcn_rsqf(var + EPS); }
; #pragma unroll
;     for (int i = 0; i < 8; ++i) { const int id = tid + 512 * i, t = id >> 5, s4 = (id & 31) * 4; const f32x4 v = *(const f32x4*)(sw + (size_t)g * 16384 + t * 128 + s4);
;         u32x2 w; w.x = cvt_pk_bf16(v[0], v[1]); w.y = cvt_pk_bf16(v[2], v[3]); *(LAS u32x2*)(lds + SG_WL + t * 272 + s4 * 2) = w; }
.LBB0_851:
	s_cmpk_gt_i32 s39, 0x3ff
	s_cbranch_scc1 .LBB0_850
	v_mov_b32_e32 v0, v1
	v_readlane_b32 s34, v253, 14
	v_mbcnt_lo_u32_b32 v0, -1, v0
	v_mbcnt_hi_u32_b32 v34, -1, v0
	s_and_b32 s45, s39, 7
	v_add_u32_e32 v6, s34, v34
	s_and_b32 s43, s42, 0xffffff80
	s_lshl_b32 s44, s45, 7
	s_lshl_b32 s34, s45, 8
	v_lshlrev_b32_e32 v0, 3, v34
	s_add_u32 s34, s30, s34
	v_and_b32_e32 v38, 0x78, v0
	s_addc_u32 s35, s36, 0
	v_lshlrev_b32_e32 v0, 1, v38
	v_lshl_add_u64 v[2:3], s[34:35], 0, v[0:1]
	v_ashrrev_i32_e32 v0, 4, v6
	v_add_u32_e32 v37, 0x200, v6
	v_add_u32_e32 v4, s43, v0
	v_ashrrev_i32_e32 v0, 4, v37
	v_ashrrev_i32_e32 v5, 31, v4
	v_add_u32_e32 v8, s43, v0
	v_lshlrev_b64 v[4:5], 11, v[4:5]
	v_ashrrev_i32_e32 v9, 31, v8
	v_add_u32_e32 v36, 0x400, v6
	v_lshl_add_u64 v[4:5], v[2:3], 0, v[4:5]
	v_lshlrev_b64 v[8:9], 11, v[8:9]
	v_ashrrev_i32_e32 v0, 4, v36
	v_add_u32_e32 v35, 0x600, v6
	v_lshl_add_u64 v[8:9], v[2:3], 0, v[8:9]
	global_load_dwordx4 v[30:33], v[4:5], off
	global_load_dwordx4 v[26:29], v[8:9], off
	v_add_u32_e32 v4, s43, v0
	v_ashrrev_i32_e32 v0, 4, v35
	v_add_u32_e32 v8, s43, v0
	v_ashrrev_i32_e32 v5, 31, v4
	v_ashrrev_i32_e32 v9, 31, v8
	v_lshlrev_b64 v[4:5], 11, v[4:5]
	v_lshlrev_b64 v[8:9], 11, v[8:9]
	v_lshl_add_u64 v[4:5], v[2:3], 0, v[4:5]
	v_lshl_add_u64 v[2:3], v[2:3], 0, v[8:9]
	global_load_dwordx4 v[18:21], v[4:5], off
	s_nop 0
	global_load_dwordx4 v[2:5], v[2:3], off
	v_lshlrev_b32_e32 v0, 2, v34
	s_lshl_b32 s34, s45, 16
	v_and_b32_e32 v7, 0x7c, v0
	s_add_u32 s34, s16, s34
	s_addc_u32 s35, s18, 0
	v_lshlrev_b32_e32 v0, 2, v7
	v_lshl_add_u64 v[12:13], s[34:35], 0, v[0:1]
	v_lshl_add_u32 v174, v7, 1, 0
	v_ashrrev_i32_e32 v7, 5, v6
	v_lshlrev_b32_e32 v8, 7, v7
	v_ashrrev_i32_e32 v9, 31, v8
	v_lshl_add_u64 v[8:9], v[8:9], 2, v[12:13]
	global_load_dwordx4 v[196:199], v[8:9], off
	v_mov_b32_e32 v228, v7
	s_movk_i32 s45, 0x110
	v_ashrrev_i32_e32 v229, 5, v37
	v_lshlrev_b32_e32 v8, 7, v229
	v_ashrrev_i32_e32 v9, 31, v8
	v_lshl_add_u64 v[8:9], v[8:9], 2, v[12:13]
	global_load_dwordx4 v[200:203], v[8:9], off
	v_ashrrev_i32_e32 v230, 5, v36
	v_lshlrev_b32_e32 v8, 7, v230
	v_ashrrev_i32_e32 v9, 31, v8
	v_lshl_add_u64 v[8:9], v[8:9], 2, v[12:13]
	global_load_dwordx4 v[204:207], v[8:9], off
	v_ashrrev_i32_e32 v231, 5, v35
	v_lshlrev_b32_e32 v8, 7, v231
	v_ashrrev_i32_e32 v9, 31, v8
	v_lshl_add_u64 v[8:9], v[8:9], 2, v[12:13]
	global_load_dwordx4 v[208:211], v[8:9], off
	v_add_u32_e32 v232, 0x800, v6
	v_ashrrev_i32_e32 v232, 5, v232
	v_lshlrev_b32_e32 v8, 7, v232
	v_ashrrev_i32_e32 v9, 31, v8
	v_lshl_add_u64 v[8:9], v[8:9], 2, v[12:13]
	global_load_dwordx4 v[212:215], v[8:9], off
	v_add_u32_e32 v233, 0xa00, v6
	v_ashrrev_i32_e32 v233, 5, v233
	v_lshlrev_b32_e32 v8, 7, v233
	v_ashrrev_i32_e32 v9, 31, v8
	v_lshl_add_u64 v[8:9], v[8:9], 2, v[12:13]
	global_load_dwordx4 v[216:219], v[8:9], off
	v_add_u32_e32 v234, 0xc00, v6
	v_ashrrev_i32_e32 v234, 5, v234
	v_lshlrev_b32_e32 v8, 7, v234
	v_ashrrev_i32_e32 v9, 31, v8
	v_lshl_add_u64 v[8:9], v[8:9], 2, v[12:13]
	global_load_dwordx4 v[220:223], v[8:9], off
	v_add_u32_e32 v235, 0xe00, v6
	v_ashrrev_i32_e32 v235, 5, v235
	v_lshlrev_b32_e32 v8, 7, v235
	v_ashrrev_i32_e32 v9, 31, v8
	v_lshl_add_u64 v[8:9], v[8:9], 2, v[12:13]
	global_load_dwordx4 v[224:227], v[8:9], off
	v_mov_b32_e32 v175, 0
	s_lshl_b32 s34, s44, 2
	s_add_u32 s46, s19, s34
	s_addc_u32 s47, s20, 0
	s_add_u32 s48, s21, s34
	s_addc_u32 s49, s28, 0
	v_lshlrev_b32_e32 v192, 2, v38
	global_load_dwordx4 v[176:179], v192, s[46:47] offset:16
	global_load_dwordx4 v[180:183], v192, s[46:47]
	global_load_dwordx4 v[184:187], v192, s[48:49] offset:16
	global_load_dwordx4 v[188:191], v192, s[48:49]
	s_movk_i32 s34, 0x80
	v_cmp_gt_i32_e32 vcc, s34, v6
	s_and_saveexec_b64 s[34:35], vcc
	s_cbranch_execz .LBB0_849
	v_add_u32_e32 v8, s43, v6
	v_ashrrev_i32_e32 v9, 31, v8
	v_lshlrev_b64 v[8:9], 7, v[8:9]
	v_lshl_add_u64 v[16:17], s[14:15], 0, v[8:9]
	global_load_dwordx4 v[8:11], v[16:17], off offset:48
	global_load_dwordx4 v[12:15], v[16:17], off offset:32
	global_load_dwordx4 v[22:25], v[16:17], off offset:16
	global_load_dwordx4 v[40:43], v[16:17], off
	global_load_dwordx4 v[52:55], v[16:17], off offset:112
	global_load_dwordx4 v[56:59], v[16:17], off offset:96
	global_load_dwordx4 v[60:63], v[16:17], off offset:80
	global_load_dwordx4 v[64:67], v[16:17], off offset:64
	s_mov_b32 s46, 0x3a800000
	s_waitcnt vmcnt(7)
	v_add_f32_e32 v8, v8, v10
	s_waitcnt vmcnt(6)
	v_add_f32_e32 v12, v12, v14
	s_waitcnt vmcnt(5)
	v_add_f32_e32 v22, v22, v24
	s_waitcnt vmcnt(4)
	v_add_f32_e32 v0, v40, v42
	v_add_f32_e32 v0, 0, v0
	v_add_f32_e32 v7, v41, v43
	v_add_f32_e32 v7, 0, v7
	v_add_f32_e32 v0, v0, v22
	v_add_f32_e32 v22, v23, v25
	v_add_f32_e32 v7, v7, v22
	v_add_f32_e32 v0, v0, v12
	v_add_f32_e32 v12, v13, v15
	v_add_f32_e32 v7, v7, v12
	v_add_f32_e32 v0, v0, v8
	v_add_f32_e32 v8, v9, v11
	v_add_f32_e32 v7, v7, v8
	s_waitcnt vmcnt(3)
	v_add_f32_e32 v52, v52, v54
	s_waitcnt vmcnt(2)
	v_add_f32_e32 v56, v56, v58
	s_waitcnt vmcnt(0)
	v_add_f32_e32 v16, v64, v66
	v_add_f32_e32 v0, v0, v16
	v_add_f32_e32 v16, v65, v67
	v_add_f32_e32 v7, v7, v16
	v_add_f32_e32 v16, v60, v62
	v_add_f32_e32 v0, v0, v16
	v_add_f32_e32 v16, v61, v63
	v_add_f32_e32 v7, v7, v16
	v_add_f32_e32 v0, v0, v56
	v_add_f32_e32 v56, v57, v59
	v_add_f32_e32 v7, v7, v56
	v_add_f32_e32 v0, v0, v52
	v_add_f32_e32 v52, v53, v55
	v_add_f32_e32 v7, v7, v52
	v_mul_f32_e32 v8, 0x3a800000, v0
	v_mul_f32_e32 v0, v8, v8
	v_fma_f32 v0, v7, s46, -v0
	v_add_f32_e32 v0, 0x358637bd, v0
	v_rsq_f32_e32 v9, v0
	v_lshl_add_u32 v7, v6, 3, 0
	v_add_u32_e32 v7, 0x11000, v7
	ds_write_b64 v7, v[8:9]
	s_branch .LBB0_849
